# v068 plus: row-half K-loop no longer stages the never-read A half-tile (12 instead of 16 LDS-DMA loads per iteration, waits vmcnt(6))
# baseline (speedup 1.0000x reference)
; #define PG8_STAGE(bufoff, gbase, voff) do { _Pragma("unroll") for (int _i = 0; _i < 2; ++_i) \
;         __builtin_amdgcn_global_load_lds((const unsigned*)((const char*)(gbase) + (voff)[_i]), (LAS unsigned*)(lds + (bufoff) + ldsw + _i * 8192), 16, 0, 0); } while (0)
; #define PG8_LDA(dst, b, h) do { _Pragma("unroll") for (int m = 0; m < 4; ++m) _Pragma("unroll") for (int k = 0; k < 2; ++k) dst[m][k] = *(const LAS bf16x8*)(lds + PG8_SA(b, h) + aoff + m * 2048 + k * 1024); } while (0)
; #define PG8_LDB(dst, b, h) do { _Pragma("unroll") for (int n = 0; n < 2; ++n) _Pragma("unroll") for (int k = 0; k < 2; ++k) dst[n][k] = *(const LAS bf16x8*)(lds + PG8_SB(b, h) + boff + n * 2048 + k * 1024); } while (0)
; #define PG8_MMA(ai, bj, At, Bt) do { __builtin_amdgcn_s_setprio(1); _Pragma("unroll") for (int m = 0; m < 4; ++m) _Pragma("unroll") for (int n = 0; n < 2; ++n) _Pragma("unroll") for (int k = 0; k < 2; ++k) \
;         acc[ai][bj][m][n] = __builtin_amdgcn_mfma_f32_16x16x32_bf16(Bt[n][k], At[m][k], acc[ai][bj][m][n], 0, 0, 0); __builtin_amdgcn_s_setprio(0); } while (0)
; template <class Epi, bool ALIGN_EPI, bool SP2, bool ROWHALF = false>
; DI void gemm_phase(LAS unsigned char* lds, const Gemm g, const StaticOrder& S, const Epi& E) {
;     ...
;             PG8_LDB(B0, 0, 0); PG8_LDB(B1, 0, 1); PG8_SCHED; PG8_LDA(At, 0, 0); PG8_STAGE(PG8_SA(1, 1), a1 + hA1, voffA);
;             PG8_WAIT_V(8); PG8_WAIT_L(0); PG8_BAR; PG8_MMA(0, 0, At, B0); PG8_MMA(0, 1, At, B1); PG8_BAR; PG8_SCHED;
;             if constexpr (!ROWHALF) { PG8_LDA(At, 0, 1); } PG8_STAGE(PG8_SB(0, 0), b2, voffB); PG8_STAGE(PG8_SB(0, 1), b2 + hstepB, voffB); PG8_STAGE(PG8_SA(0, 0), a2 + hA0, voffA);
;             PG8_WAIT_V(8); PG8_WAIT_L(0); PG8_BAR; if constexpr (!ROWHALF) { PG8_MMA(1, 0, At, B0); PG8_MMA(1, 1, At, B1); } PG8_BAR; PG8_SCHED;
;             PG8_LDB(B0, 1, 0); PG8_LDB(B1, 1, 1); PG8_SCHED; PG8_LDA(At, 1, 0); PG8_STAGE(PG8_SA(0, 1), a2 + hA1, voffA);
;             PG8_WAIT_V(8); PG8_WAIT_L(0); PG8_BAR; PG8_MMA(0, 0, At, B0); PG8_MMA(0, 1, At, B1); PG8_BAR; PG8_SCHED;
;             if constexpr (!ROWHALF) { PG8_LDA(At, 1, 1); } PG8_STAGE(PG8_SB(1, 0), b3, voffB); PG8_STAGE(PG8_SB(1, 1), b3 + hstepB, voffB); PG8_STAGE(PG8_SA(1, 0), a3 + hA0, voffA);
;             PG8_WAIT_V(8); PG8_WAIT_L(0); PG8_BAR; if constexpr (!ROWHALF) { PG8_MMA(1, 0, At, B0); PG8_MMA(1, 1, At, B1); } PG8_BAR; PG8_SCHED;
.LBB0_251:
	s_add_u32 s22, s28, s18
	s_addc_u32 s23, s29, s19
	s_add_u32 s22, s22, 0x18080100
	s_addc_u32 s23, s23, 0
	s_add_u32 s36, s4, s18
	s_addc_u32 s37, s5, s19
	s_add_i32 s40, 0, 0x10000
	s_cmpk_eq_i32 s18, 0xf00
	s_cselect_b32 s41, s13, s23
	s_cselect_b32 s42, s7, s22
	s_cselect_b32 s23, s17, s37
	s_cselect_b32 s22, s16, s36
	s_add_i32 s43, 0, 0x14000
	v_add_u32_e32 v90, s40, v76
	v_add_u32_e32 v94, s43, v76
	ds_read_b128 v[78:81], v90
	ds_read_b128 v[82:85], v90 offset:1024
	ds_read_b128 v[86:89], v90 offset:2048
	ds_read_b128 v[90:93], v90 offset:3072
	ds_read_b128 v[98:101], v94
	ds_read_b128 v[102:105], v94 offset:1024
	ds_read_b128 v[106:109], v94 offset:2048
	ds_read_b128 v[110:113], v94 offset:3072
	ds_read_b128 v[114:117], v77
	ds_read_b128 v[118:121], v77 offset:1024
	ds_read_b128 v[122:125], v77 offset:2048
	ds_read_b128 v[126:129], v77 offset:3072
	ds_read_b128 v[130:133], v77 offset:4096
	ds_read_b128 v[134:137], v77 offset:5120
	ds_read_b128 v[138:141], v77 offset:6144
	ds_read_b128 v[142:145], v77 offset:7168
	s_waitcnt vmcnt(6)
	s_waitcnt lgkmcnt(0)
	s_setprio 1
	v_mfma_f32_16x16x32_bf16 v[60:63], v[78:81], v[114:117], v[60:63]
	v_mfma_f32_16x16x32_bf16 v[52:55], v[86:89], v[114:117], v[52:55]
	v_mfma_f32_16x16x32_bf16 v[44:47], v[78:81], v[122:125], v[44:47]
	v_mfma_f32_16x16x32_bf16 v[36:39], v[86:89], v[122:125], v[36:39]
	s_barrier
	v_mfma_f32_16x16x32_bf16 v[28:31], v[78:81], v[130:133], v[28:31]
	v_mfma_f32_16x16x32_bf16 v[20:23], v[86:89], v[130:133], v[20:23]
	v_mfma_f32_16x16x32_bf16 v[12:15], v[78:81], v[138:141], v[12:15]
	v_mfma_f32_16x16x32_bf16 v[4:7], v[86:89], v[138:141], v[4:7]
	v_mfma_f32_16x16x32_bf16 v[60:63], v[82:85], v[118:121], v[60:63]
	v_mfma_f32_16x16x32_bf16 v[52:55], v[90:93], v[118:121], v[52:55]
	v_mfma_f32_16x16x32_bf16 v[44:47], v[82:85], v[126:129], v[44:47]
	v_mfma_f32_16x16x32_bf16 v[36:39], v[90:93], v[126:129], v[36:39]
	v_mfma_f32_16x16x32_bf16 v[28:31], v[82:85], v[134:137], v[28:31]
	v_mfma_f32_16x16x32_bf16 v[20:23], v[90:93], v[134:137], v[20:23]
	v_mfma_f32_16x16x32_bf16 v[12:15], v[82:85], v[142:145], v[12:15]
	v_mfma_f32_16x16x32_bf16 v[4:7], v[90:93], v[142:145], v[4:7]
	s_setprio 0
	s_setprio 1
	v_mfma_f32_16x16x32_bf16 v[56:59], v[98:101], v[114:117], v[56:59]
	v_mfma_f32_16x16x32_bf16 v[48:51], v[106:109], v[114:117], v[48:51]
	v_mfma_f32_16x16x32_bf16 v[40:43], v[98:101], v[122:125], v[40:43]
	v_mfma_f32_16x16x32_bf16 v[32:35], v[106:109], v[122:125], v[32:35]
	v_mfma_f32_16x16x32_bf16 v[24:27], v[98:101], v[130:133], v[24:27]
	v_mfma_f32_16x16x32_bf16 v[16:19], v[106:109], v[130:133], v[16:19]
	v_mfma_f32_16x16x32_bf16 v[8:11], v[98:101], v[138:141], v[8:11]
	v_mfma_f32_16x16x32_bf16 v[0:3], v[106:109], v[138:141], v[0:3]
	v_mfma_f32_16x16x32_bf16 v[56:59], v[102:105], v[118:121], v[56:59]
	v_mfma_f32_16x16x32_bf16 v[48:51], v[110:113], v[118:121], v[48:51]
	v_mfma_f32_16x16x32_bf16 v[40:43], v[102:105], v[126:129], v[40:43]
	v_mfma_f32_16x16x32_bf16 v[32:35], v[110:113], v[126:129], v[32:35]
	v_mfma_f32_16x16x32_bf16 v[24:27], v[102:105], v[134:137], v[24:27]
	v_mfma_f32_16x16x32_bf16 v[16:19], v[110:113], v[134:137], v[16:19]
	v_mfma_f32_16x16x32_bf16 v[8:11], v[102:105], v[142:145], v[8:11]
	v_mfma_f32_16x16x32_bf16 v[0:3], v[110:113], v[142:145], v[0:3]
	s_setprio 0
	s_barrier
	s_add_i32 s36, s40, s12
	v_lshl_add_u64 v[94:95], s[22:23], 0, v[96:97]
	s_mov_b32 m0, s36
	v_lshl_add_u64 v[146:147], s[22:23], 0, v[68:69]
	global_load_lds_dwordx4 v[94:95], off
	s_add_i32 m0, s36, 0x2000
	s_add_u32 s36, s22, 0x80000
	s_addc_u32 s37, s23, 0
	s_add_i32 s40, s43, s12
	global_load_lds_dwordx4 v[146:147], off
	v_lshl_add_u64 v[78:79], s[36:37], 0, v[96:97]
	s_mov_b32 m0, s40
	s_nop 0
	global_load_lds_dwordx4 v[78:79], off
	s_add_i32 m0, s40, 0x2000
	v_lshl_add_u64 v[78:79], s[36:37], 0, v[68:69]
	s_add_u32 s36, s42, s3
	s_addc_u32 s37, s41, 0
	global_load_lds_dwordx4 v[78:79], off
	v_lshl_add_u64 v[148:149], s[36:37], 0, v[64:65]
	s_mov_b32 m0, s6
	v_lshl_add_u64 v[150:151], s[36:37], 0, v[66:67]
	global_load_lds_dwordx4 v[148:149], off
	s_mov_b32 m0, s20
	s_nop 0
	global_load_lds_dwordx4 v[150:151], off
	s_waitcnt vmcnt(6)
	s_waitcnt lgkmcnt(0)
	s_barrier
; #define PG8_STAGE(bufoff, gbase, voff) do { _Pragma("unroll") for (int _i = 0; _i < 2; ++_i) \
;         __builtin_amdgcn_global_load_lds((const unsigned*)((const char*)(gbase) + (voff)[_i]), (LAS unsigned*)(lds + (bufoff) + ldsw + _i * 8192), 16, 0, 0); } while (0)
; #define PG8_LDA(dst, b, h) do { _Pragma("unroll") for (int m = 0; m < 4; ++m) _Pragma("unroll") for (int k = 0; k < 2; ++k) dst[m][k] = *(const LAS bf16x8*)(lds + PG8_SA(b, h) + aoff + m * 2048 + k * 1024); } while (0)
; #define PG8_LDB(dst, b, h) do { _Pragma("unroll") for (int n = 0; n < 2; ++n) _Pragma("unroll") for (int k = 0; k < 2; ++k) dst[n][k] = *(const LAS bf16x8*)(lds + PG8_SB(b, h) + boff + n * 2048 + k * 1024); } while (0)
; #define PG8_MMA(ai, bj, At, Bt) do { __builtin_amdgcn_s_setprio(1); _Pragma("unroll") for (int m = 0; m < 4; ++m) _Pragma("unroll") for (int n = 0; n < 2; ++n) _Pragma("unroll") for (int k = 0; k < 2; ++k) \
;         acc[ai][bj][m][n] = __builtin_amdgcn_mfma_f32_16x16x32_bf16(Bt[n][k], At[m][k], acc[ai][bj][m][n], 0, 0, 0); __builtin_amdgcn_s_setprio(0); } while (0)
; template <class Epi, bool ALIGN_EPI, bool SP2, bool ROWHALF = false>
; DI void gemm_phase(LAS unsigned char* lds, const Gemm g, const StaticOrder& S, const Epi& E) {
;     ...
;             PG8_LDB(B0, 0, 0); PG8_LDB(B1, 0, 1); PG8_SCHED; PG8_LDA(At, 0, 0); PG8_STAGE(PG8_SA(1, 1), a1 + hA1, voffA);
;             PG8_WAIT_V(8); PG8_WAIT_L(0); PG8_BAR; PG8_MMA(0, 0, At, B0); PG8_MMA(0, 1, At, B1); PG8_BAR; PG8_SCHED;
;             if constexpr (!ROWHALF) { PG8_LDA(At, 0, 1); } PG8_STAGE(PG8_SB(0, 0), b2, voffB); PG8_STAGE(PG8_SB(0, 1), b2 + hstepB, voffB); PG8_STAGE(PG8_SA(0, 0), a2 + hA0, voffA);
;             PG8_WAIT_V(8); PG8_WAIT_L(0); PG8_BAR; if constexpr (!ROWHALF) { PG8_MMA(1, 0, At, B0); PG8_MMA(1, 1, At, B1); } PG8_BAR; PG8_SCHED;
;             PG8_LDB(B0, 1, 0); PG8_LDB(B1, 1, 1); PG8_SCHED; PG8_LDA(At, 1, 0); PG8_STAGE(PG8_SA(0, 1), a2 + hA1, voffA);
;             PG8_WAIT_V(8); PG8_WAIT_L(0); PG8_BAR; PG8_MMA(0, 0, At, B0); PG8_MMA(0, 1, At, B1); PG8_BAR; PG8_SCHED;
;             if constexpr (!ROWHALF) { PG8_LDA(At, 1, 1); } PG8_STAGE(PG8_SB(1, 0), b3, voffB); PG8_STAGE(PG8_SB(1, 1), b3 + hstepB, voffB); PG8_STAGE(PG8_SA(1, 0), a3 + hA0, voffA);
;             PG8_WAIT_V(8); PG8_WAIT_L(0); PG8_BAR; if constexpr (!ROWHALF) { PG8_MMA(1, 0, At, B0); PG8_MMA(1, 1, At, B1); } PG8_BAR; PG8_SCHED;
	s_barrier
	s_add_i32 s40, 0, 0x18000
	s_add_i32 s43, 0, 0x1c000
	v_add_u32_e32 v90, s40, v76
	v_add_u32_e32 v110, s43, v76
	ds_read_b128 v[78:81], v90
	ds_read_b128 v[82:85], v90 offset:1024
	ds_read_b128 v[86:89], v90 offset:2048
	ds_read_b128 v[90:93], v90 offset:3072
	ds_read_b128 v[98:101], v110
	ds_read_b128 v[102:105], v110 offset:1024
	ds_read_b128 v[106:109], v110 offset:2048
	ds_read_b128 v[110:113], v110 offset:3072
	ds_read_b128 v[114:117], v77 offset:32768
	ds_read_b128 v[118:121], v77 offset:33792
	ds_read_b128 v[122:125], v77 offset:34816
	ds_read_b128 v[126:129], v77 offset:35840
	ds_read_b128 v[130:133], v77 offset:36864
	ds_read_b128 v[134:137], v77 offset:37888
	ds_read_b128 v[138:141], v77 offset:38912
	ds_read_b128 v[142:145], v77 offset:39936
	s_waitcnt vmcnt(6)
	s_waitcnt lgkmcnt(0)
	s_setprio 1
	v_mfma_f32_16x16x32_bf16 v[60:63], v[78:81], v[114:117], v[60:63]
	v_mfma_f32_16x16x32_bf16 v[52:55], v[86:89], v[114:117], v[52:55]
	v_mfma_f32_16x16x32_bf16 v[44:47], v[78:81], v[122:125], v[44:47]
	v_mfma_f32_16x16x32_bf16 v[36:39], v[86:89], v[122:125], v[36:39]
	s_barrier
	v_mfma_f32_16x16x32_bf16 v[28:31], v[78:81], v[130:133], v[28:31]
	v_mfma_f32_16x16x32_bf16 v[20:23], v[86:89], v[130:133], v[20:23]
	v_mfma_f32_16x16x32_bf16 v[12:15], v[78:81], v[138:141], v[12:15]
	v_mfma_f32_16x16x32_bf16 v[4:7], v[86:89], v[138:141], v[4:7]
	v_mfma_f32_16x16x32_bf16 v[60:63], v[82:85], v[118:121], v[60:63]
	v_mfma_f32_16x16x32_bf16 v[52:55], v[90:93], v[118:121], v[52:55]
	v_mfma_f32_16x16x32_bf16 v[44:47], v[82:85], v[126:129], v[44:47]
	v_mfma_f32_16x16x32_bf16 v[36:39], v[90:93], v[126:129], v[36:39]
	v_mfma_f32_16x16x32_bf16 v[28:31], v[82:85], v[134:137], v[28:31]
	v_mfma_f32_16x16x32_bf16 v[20:23], v[90:93], v[134:137], v[20:23]
	v_mfma_f32_16x16x32_bf16 v[12:15], v[82:85], v[142:145], v[12:15]
	v_mfma_f32_16x16x32_bf16 v[4:7], v[90:93], v[142:145], v[4:7]
	s_setprio 0
	s_setprio 1
	v_mfma_f32_16x16x32_bf16 v[56:59], v[98:101], v[114:117], v[56:59]
	v_mfma_f32_16x16x32_bf16 v[48:51], v[106:109], v[114:117], v[48:51]
	v_mfma_f32_16x16x32_bf16 v[40:43], v[98:101], v[122:125], v[40:43]
	v_mfma_f32_16x16x32_bf16 v[32:35], v[106:109], v[122:125], v[32:35]
	v_mfma_f32_16x16x32_bf16 v[24:27], v[98:101], v[130:133], v[24:27]
	v_mfma_f32_16x16x32_bf16 v[16:19], v[106:109], v[130:133], v[16:19]
	v_mfma_f32_16x16x32_bf16 v[8:11], v[98:101], v[138:141], v[8:11]
	v_mfma_f32_16x16x32_bf16 v[0:3], v[106:109], v[138:141], v[0:3]
	v_mfma_f32_16x16x32_bf16 v[56:59], v[102:105], v[118:121], v[56:59]
	v_mfma_f32_16x16x32_bf16 v[48:51], v[110:113], v[118:121], v[48:51]
	v_mfma_f32_16x16x32_bf16 v[40:43], v[102:105], v[126:129], v[40:43]
	v_mfma_f32_16x16x32_bf16 v[32:35], v[110:113], v[126:129], v[32:35]
	v_mfma_f32_16x16x32_bf16 v[24:27], v[102:105], v[134:137], v[24:27]
	v_mfma_f32_16x16x32_bf16 v[16:19], v[110:113], v[134:137], v[16:19]
	v_mfma_f32_16x16x32_bf16 v[8:11], v[102:105], v[142:145], v[8:11]
	v_mfma_f32_16x16x32_bf16 v[0:3], v[110:113], v[142:145], v[0:3]
	s_setprio 0
	s_barrier
	s_add_i32 s36, s40, s12
	v_lshl_add_u64 v[78:79], v[94:95], 0, s[38:39]
	s_mov_b32 m0, s36
	s_nop 0
	global_load_lds_dwordx4 v[78:79], off
	s_add_i32 m0, s36, 0x2000
	s_add_u32 s22, s22, 0x80080
	v_lshl_add_u64 v[78:79], v[146:147], 0, s[38:39]
	s_addc_u32 s23, s23, 0
	s_add_i32 s36, s43, s12
	global_load_lds_dwordx4 v[78:79], off
	v_lshl_add_u64 v[78:79], s[22:23], 0, v[96:97]
	s_mov_b32 m0, s36
	s_nop 0
	global_load_lds_dwordx4 v[78:79], off
	v_lshl_add_u64 v[78:79], s[22:23], 0, v[68:69]
	s_add_i32 m0, s36, 0x2000
	s_nop 0
	global_load_lds_dwordx4 v[78:79], off
	v_lshl_add_u64 v[78:79], v[148:149], 0, s[38:39]
	s_mov_b32 m0, s26
	s_nop 0
	global_load_lds_dwordx4 v[78:79], off
	v_lshl_add_u64 v[78:79], v[150:151], 0, s[38:39]
	s_mov_b32 m0, s27
	s_nop 0
	global_load_lds_dwordx4 v[78:79], off
	s_waitcnt vmcnt(6)
	s_waitcnt lgkmcnt(0)
	s_barrier
	s_barrier
	s_add_i32 s31, s31, 2
	s_add_u32 s18, s18, 0x100
	s_addc_u32 s19, s19, 0
	s_cmp_gt_u32 s31, 29
	s_cbranch_scc0 .LBB0_251
	s_cmpk_lt_u32 s9, 0x100
	s_cbranch_scc0 .LBB0_254
	s_barrier
